# attention K/V DMA with running tile bases (shorter DMA issue group) + DK forward-substitution rewrite
# speedup vs baseline: 1.0127x; 1.0045x over previous
; __device__ __forceinline__ int v_st(int k, int c) { const int kk = (k & ~0xC) | ((k & 4) << 1) | ((k & 8) >> 1); return ((kk >> 3) * 4 + (c >> 5)) * 512 + ((kk & 7) * 32 + (c & 31)) * 2; }
; __device__ __forceinline__ int v_rd_base(int lane) { return ((lane & 3) << 3) | (((lane >> 2) & 3) << 6) | (((lane >> 4) & 1) << 5) | (((lane >> 5) & 1) << 8); }
; #define KLOAD(k0) do { ks0 = *reinterpret_cast<const bf16x8*>(&Kh[(long)((k0) + sr) * LDK + sc]); ks1 = *reinterpret_cast<const bf16x8*>(&Kh[(long)((k0) + 32 + sr) * LDK + sc]); } while (0)
; #define KWRITE(b) do { const int kc = sc * 2; *(bf16x8*)(K_lds + (b) * 16384 + KSWZ(sr, kc)) = ks0; *(bf16x8*)(K_lds + (b) * 16384 + KSWZ(32 + sr, kc)) = ks1; } while (0)
; template <int LDQ, int LDK, int LDO>
; __device__ __forceinline__ void attn_pair_body(const bf16* __restrict__ Qb, const bf16* __restrict__ Kh, const bf16* __restrict__ Vh, float* __restrict__ Ob, int NT, char* lds, int tid_in) {
;   int tid_l = tid_in; asm volatile("" : "+v"(tid_l)); const int tid = tid_l, wid = __builtin_amdgcn_readfirstlane(tid >> 6), lane = tid & 63, r32 = lane & 31, hi = lane >> 5;
;   const int rg = wid & 3, vhw = wid >> 2;
;   char* V_lds = lds + AP_V; char* K_lds = lds + AP_K;
;   char* Pp = lds + AP_P + rg * 8192;
;   float* ALp = (float*)(lds + AP_AL) + rg * 64; float* Mp = (float*)(lds + AP_M) + rg * 32; unsigned* FLp = (unsigned*)(lds + AP_FL) + rg * 2; float* LXp = (float*)(lds + AP_LX) + rg * 64;
;   float m_reg = -1e30f, l_reg = 0.f; f32x16 o[4] = {}; bf16x8 qr[8];
;   const bf16* Qw = Qb + (long)(rg * QBLK + r32) * LDQ + hi * 8;
; #pragma unroll
;   for (int d0 = 0; d0 < 8; ++d0) qr[d0] = *reinterpret_cast<const bf16x8*>(Qw + d0 * 16);
;   const int sr = tid >> 4, sc = (tid & 15) * 8, vst0 = v_st(sr, sc), vst1 = v_st(32 + sr, sc);
;   const int vb0 = (int)(uintptr_t)(V_lds + vhw * 16384) + v_rd_base(lane);
;   bf16x8 ks0, ks1, vs00, vs01, vs10, vs11;
;     ...
;   KLOAD(0); asm volatile("s_waitcnt vmcnt(0)" ::: "memory"); KWRITE(0);
;   if (NT > 1) { KLOAD(KVBLK); asm volatile("s_waitcnt vmcnt(0)" ::: "memory"); KWRITE(1); }
;   if (NT > 2) KLOAD(2 * KVBLK);
;   VLOAD(0);
;   __syncthreads();
;   f32x16 p0 = f32x16{}, p1 = f32x16{};
;   if (vhw == 0) { qkt_batched(p0, p1, (const bf16*)K_lds, qr, r32, hi); }
;   __syncthreads();
.LBB0_1015:
	v_and_b32_e32 v5, 0xfffff0, v188
	v_lshlrev_b32_e32 v7, 1, v188
	v_and_or_b32 v5, v7, 8, v5
	v_lshrrev_b32_e32 v7, 1, v188
	v_lshrrev_b32_e32 v5, 1, v5
	v_lshrrev_b32_e32 v8, 5, v15
	v_and_b32_e32 v9, 3, v188
	s_lshl_b32 s10, s10, 2
	v_or_b32_e32 v5, v5, v8
	v_and_or_b32 v7, v7, 4, v9
	s_add_i32 s10, s10, 0
	v_lshlrev_b32_e32 v5, 9, v5
	v_lshlrev_b32_e32 v7, 6, v7
	v_and_b32_e32 v9, 48, v4
	s_add_i32 s12, s10, 0x20400
	s_lshl_b32 s10, s5, 8
	v_or3_b32 v201, v5, v7, v9
	v_and_b32_e32 v5, 0xfffff0, v189
	v_lshlrev_b32_e32 v10, 1, v189
	s_add_i32 s10, s10, 0
	v_and_or_b32 v5, v10, 8, v5
	s_lshl_b32 s9, s5, 13
	s_add_i32 s28, s10, 0x20000
	s_lshl_b32 s10, s5, 3
	v_lshrrev_b32_e32 v5, 1, v5
	v_and_b32_e32 v6, 63, v14
	s_ashr_i32 s8, s8, 8
	s_add_i32 s9, s9, 0
	s_add_i32 s10, s10, 0
	v_or_b32_e32 v5, v5, v8
	s_ashr_i32 s19, s18, 31
	s_add_i32 s15, s9, 0x18000
	s_lshl_b32 s9, s5, 6
	s_add_i32 s10, s10, 0x20600
	v_lshlrev_b32_e32 v5, 9, v5
	s_lshl_b32 s13, s8, 14
	v_lshlrev_b32_e32 v203, 4, v6
	v_or3_b32 v202, v5, v7, v9
	s_cmp_lg_u32 0, -1
	v_lshlrev_b32_e32 v5, 3, v6
	v_and_b32_e32 v7, 0xc0, v203
	v_lshlrev_b32_e32 v8, 1, v6
	s_cselect_b32 s14, 0, 0
	v_and_or_b32 v7, v5, 24, v7
	v_and_b32_e32 v8, 32, v8
	v_and_b32_e32 v5, 0x100, v5
	s_add_i32 s14, s14, s13
	v_or3_b32 v5, v7, v8, v5
	v_add_u32_e32 v211, s14, v5
	v_mov_b32_e32 v5, v3
	v_lshl_add_u64 v[182:183], s[20:21], 0, v[4:5]
	s_mov_b64 s[60:61], s[20:21]
	s_lshl_b32 s20, s8, 7
	v_lshlrev_b32_e32 v180, 2, v187
	s_add_i32 s14, s28, s20
	v_mov_b32_e32 v18, v3
	v_mov_b32_e32 v19, v3
	v_lshl_add_u64 v[184:185], s[38:39], 0, v[4:5]
	s_mov_b64 s[68:69], s[38:39]
	v_cmp_gt_u32_e64 s[38:39], 32, v6
	v_cmp_eq_u32_e64 s[40:41], 0, v6
	s_lshl_b32 s13, s8, 12
	v_add_u32_e32 v213, s14, v180
	s_lshl_b32 s14, s8, 2
	v_mov_b32_e32 v4, v3
	v_mov_b32_e32 v6, v3
	v_mov_b32_e32 v7, v3
	v_mov_b32_e32 v8, v3
	v_mov_b32_e32 v9, v3
	v_mov_b32_e32 v10, v3
	v_mov_b32_e32 v11, v3
	v_mov_b32_e32 v12, v3
	v_mov_b32_e32 v13, v3
	v_mov_b32_e32 v14, v3
	v_mov_b32_e32 v15, v3
	v_mov_b32_e32 v16, v3
	v_mov_b32_e32 v17, v3
	v_mov_b64_e32 v[66:67], v[18:19]
	v_mov_b64_e32 v[50:51], v[18:19]
	v_mov_b64_e32 v[34:35], v[18:19]
	s_mov_b32 s11, 1
	v_add_u32_e32 v212, s12, v180
	s_add_i32 s12, s4, -1
	s_add_i32 s13, s15, s13
	s_add_i32 s14, s10, s14
	v_add_u32_e32 v214, s28, v180
	v_add_u32_e32 v215, s28, v2
	v_add_u32_e32 v216, s15, v203
	v_mov_b32_e32 v218, 0
	v_mov_b32_e32 v217, 0xf149f2ca
	v_mov_b64_e32 v[64:65], v[16:17]
	v_mov_b64_e32 v[62:63], v[14:15]
	v_mov_b64_e32 v[60:61], v[12:13]
	v_mov_b64_e32 v[58:59], v[10:11]
	v_mov_b64_e32 v[56:57], v[8:9]
	v_mov_b64_e32 v[54:55], v[6:7]
	v_mov_b64_e32 v[52:53], v[4:5]
	v_mov_b64_e32 v[48:49], v[16:17]
	v_mov_b64_e32 v[46:47], v[14:15]
	v_mov_b64_e32 v[44:45], v[12:13]
	v_mov_b64_e32 v[42:43], v[10:11]
	v_mov_b64_e32 v[40:41], v[8:9]
	v_mov_b64_e32 v[38:39], v[6:7]
	v_mov_b64_e32 v[36:37], v[4:5]
	v_mov_b64_e32 v[32:33], v[16:17]
	v_mov_b64_e32 v[30:31], v[14:15]
	v_mov_b64_e32 v[28:29], v[12:13]
	v_mov_b64_e32 v[26:27], v[10:11]
	v_mov_b64_e32 v[24:25], v[8:9]
	v_mov_b64_e32 v[22:23], v[6:7]
	v_mov_b64_e32 v[20:21], v[4:5]
	v_readfirstlane_b32 s46, v186
	s_lshr_b32 s46, s46, 6
	s_lshl_b32 s32, s46, 11
	s_add_i32 s32, s32, 0x10000
	s_lshr_b32 s47, s46, 2
	s_and_b32 s29, s46, 3
	s_lshl_b32 s58, s47, 14
	s_lshl_b32 s28, s29, 12
	s_add_i32 s58, s58, s28
	v_and_b32_e32 v132, 15, v186
	v_bfe_u32 v133, v186, 4, 2
	v_xor_b32_e32 v134, v132, v133
	v_lshlrev_b32_e32 v134, 4, v134
	v_mul_u32_u24_e32 v135, 0x2400, v133
	s_mul_i32 s28, s46, 0x12000
	v_add3_u32 v172, v134, v135, s28
	v_xor_b32_e32 v134, 64, v134
	v_add3_u32 v173, v134, v135, s28
	v_add_u32_e32 v173, 0x9000, v173
	v_bfe_u32 v132, v186, 4, 1
	v_bfe_u32 v133, v186, 2, 2
	v_lshl_add_u32 v132, v132, 3, v133
	v_mul_u32_u24_e32 v132, 0x2400, v132
	v_bfe_u32 v133, v186, 5, 1
	v_lshlrev_b32_e32 v133, 6, v133
	v_and_b32_e32 v134, 3, v186
	v_lshl_add_u32 v133, v134, 4, v133
	s_mul_i32 s28, s29, 0x24000
	s_lshl_b32 s47, s47, 8
	s_add_i32 s28, s28, s47
	v_add3_u32 v174, v132, v133, s28
	s_add_u32 s74, s60, 0x90000
	s_addc_u32 s75, s61, 0
	s_sub_u32 s92, s68, 0x90000
	s_subb_u32 s93, s69, 0
	s_sub_u32 s96, s68, 0x87000
	s_subb_u32 s97, s69, 0
	s_barrier
	s_branch .LBB0_1017

; #define SBAR() __builtin_amdgcn_sched_barrier(0)
; #define KLOAD(k0) do { ks0 = *reinterpret_cast<const bf16x8*>(&Kh[(long)((k0) + sr) * LDK + sc]); ks1 = *reinterpret_cast<const bf16x8*>(&Kh[(long)((k0) + 32 + sr) * LDK + sc]); } while (0)
; #define VLOAD(k0) do { vs00 = *reinterpret_cast<const bf16x8*>(&Vh[(long)((k0) + sr) * LDK + sc]); vs01 = *reinterpret_cast<const bf16x8*>(&Vh[(long)((k0) + 32 + sr) * LDK + sc]); \
;     vs10 = *reinterpret_cast<const bf16x8*>(&Vh[(long)((k0) + sr) * LDK + 128 + sc]); vs11 = *reinterpret_cast<const bf16x8*>(&Vh[(long)((k0) + 32 + sr) * LDK + 128 + sc]); } while (0)
; #define KWRITE(b) do { const int kc = sc * 2; *(bf16x8*)(K_lds + (b) * 16384 + KSWZ(sr, kc)) = ks0; *(bf16x8*)(K_lds + (b) * 16384 + KSWZ(32 + sr, kc)) = ks1; } while (0)
; __device__ __forceinline__ void partialSM(f32x16& p0, f32x16& p1, float& m_reg, float& mn, float& alpha) {
;     ...
;   float pmax = p0[0]; for (int r = 1; r < 16; ++r) pmax = fmaxf(pmax, p0[r]); for (int r = 0; r < 16; ++r) pmax = fmaxf(pmax, p1[r]);
;   { auto rr = __builtin_amdgcn_permlane32_swap(__float_as_uint(pmax), __float_as_uint(pmax), false, false);
;     pmax = fmaxf(__uint_as_float(rr[0]), __uint_as_float(rr[1])); }
;   if (__builtin_expect(__all(pmax - m_reg <= THR / SCALE), 1)) { mn = m_reg; alpha = 1.f; }
; template <int LDQ, int LDK, int LDO>
; __device__ __forceinline__ void attn_pair_body(const bf16* __restrict__ Qb, const bf16* __restrict__ Kh, const bf16* __restrict__ Vh, float* __restrict__ Ob, int NT, char* lds, int tid_in) {
;     ...
;     const float alp_v = ALp[pb * 32 + r32], m_v = Mp[r32];
;     const bf16x8 a0 = *reinterpret_cast<const bf16x8*>(Pp + pb * 4096 + 0 * 1024 + lane * 16), a1 = *reinterpret_cast<const bf16x8*>(Pp + pb * 4096 + 1 * 1024 + lane * 16);
;     const bf16x8 a2 = *reinterpret_cast<const bf16x8*>(Pp + pb * 4096 + 2 * 1024 + lane * 16), a3 = *reinterpret_cast<const bf16x8*>(Pp + pb * 4096 + 3 * 1024 + lane * 16);
;     SBAR();
;     KWRITE(b);
;     VWRITE(b);
;     { const int tk = j + 3 < NT ? j + 3 : NT - 1, tv = j + 1 < NT ? j + 1 : NT - 1; KLOAD(tk * KVBLK); VLOAD(tv * KVBLK); }
;     SBAR();
;     if (prod) {
;       if (flp) l_reg *= alp_v;
;       if (j >= 1) m_reg = m_v;
;       float mn, al; bf16x8 pa0, pa1, pa2, pa3;
;       partialSM(p0, p1, m_reg, mn, al);
.LBB0_1023:
	v_lshl_add_u32 v156, s21, 7, v214
	v_lshl_add_u32 v157, s21, 12, v216
	ds_read_b32 v219, v156
	ds_read_b128 v[168:171], v157
	ds_read_b32 v220, v212
	ds_read_b128 v[164:167], v157 offset:1024
	ds_read_b128 v[160:163], v157 offset:2048
	ds_read_b128 v[156:159], v157 offset:3072
	s_and_b64 vcc, exec, s[42:43]
	s_cbranch_vccnz .Lpa_cons
	v_lshl_add_u32 v176, s21, 15, v211
	ds_read_b64_tr_b16 v[132:133], v176 offset:0
	ds_read_b64_tr_b16 v[134:135], v176 offset:0x800
	ds_read_b64_tr_b16 v[136:137], v176 offset:0x1000
	ds_read_b64_tr_b16 v[138:139], v176 offset:0x1800
	ds_read_b64_tr_b16 v[140:141], v176 offset:0x2000
	ds_read_b64_tr_b16 v[142:143], v176 offset:0x2800
	ds_read_b64_tr_b16 v[144:145], v176 offset:0x3000
	ds_read_b64_tr_b16 v[146:147], v176 offset:0x3800
	s_lshl_b32 s29, s28, 14
	s_lshl_b32 s28, s28, 15
	s_add_i32 s29, s29, s32
	s_add_i32 s28, s28, s58
	s_add_u32 s74, s74, 0x90000
	s_addc_u32 s75, s75, 0
	s_mov_b32 m0, s29
	s_add_u32 s92, s92, 0x90000
	s_addc_u32 s93, s93, 0
	global_load_lds_dwordx4 v172, s[74:75]
	s_add_i32 m0, s29, 0x400
	s_add_u32 s96, s96, 0x90000
	s_addc_u32 s97, s97, 0
	global_load_lds_dwordx4 v173, s[74:75]
	s_mov_b32 m0, s28
	s_nop 0
	global_load_lds_dwordx4 v174, s[92:93]
	s_add_i32 m0, s28, 0x380
	s_nop 0
	global_load_lds_dwordx4 v174, s[92:93] offset:128
	s_add_i32 m0, s28, 0x800
	s_nop 0
	global_load_lds_dwordx4 v174, s[96:97]
	s_add_i32 m0, s28, 0xb80
	s_nop 0
	global_load_lds_dwordx4 v174, s[96:97] offset:128
	v_max_f32_e32 v176, v85, v85
	v_max_f32_e32 v177, v84, v84
	v_max_f32_e32 v176, v177, v176
	v_max3_f32 v176, v176, v86, v87
	v_max3_f32 v176, v176, v88, v89
	v_max3_f32 v176, v176, v90, v91
	v_max3_f32 v176, v176, v92, v93
	v_max3_f32 v176, v176, v94, v95
	v_max3_f32 v176, v176, v96, v97
	v_max3_f32 v176, v176, v98, v99
	v_max3_f32 v176, v176, v68, v69
	v_max3_f32 v176, v176, v70, v71
	v_max3_f32 v176, v176, v72, v73
	v_max3_f32 v176, v176, v74, v75
	v_max3_f32 v176, v176, v76, v77
	v_max3_f32 v176, v176, v78, v79
	v_max3_f32 v176, v176, v80, v81
	v_max3_f32 v176, v176, v82, v83
	v_mov_b32_e32 v177, v176
	s_nop 1
	v_permlane32_swap_b32_e32 v176, v177
	v_max_f32_e32 v177, v177, v177
	v_max_f32_e32 v176, v176, v176
	s_waitcnt lgkmcnt(11)
	v_readfirstlane_b32 s29, v210
	s_cmp_lg_u32 s29, 0
	s_cselect_b64 s[62:63], -1, 0
	s_and_b64 s[62:63], s[62:63], s[56:57]
	v_cndmask_b32_e64 v217, v220, v217, s[44:45]
	v_max_f32_e32 v221, v176, v177
	v_sub_f32_e32 v176, v221, v217
	v_cmp_ge_f32_e32 vcc, s27, v176
	s_cmp_eq_u64 vcc, exec
	v_mov_b32_e32 v220, 1.0
	s_cbranch_scc0 .LBB0_1036

; #define SBAR() __builtin_amdgcn_sched_barrier(0)
; #define TRD(Lb, Hb, D0) Lb[0] = tr_read<v_rd_off(D0, 0, 0)>(vb); Hb[0] = tr_read<v_rd_off(D0, 0, 1)>(vb); Lb[1] = tr_read<v_rd_off(D0, 1, 0)>(vb); Hb[1] = tr_read<v_rd_off(D0, 1, 1)>(vb); \
;     Lb[2] = tr_read<v_rd_off(D0, 2, 0)>(vb); Hb[2] = tr_read<v_rd_off(D0, 2, 1)>(vb); Lb[3] = tr_read<v_rd_off(D0, 3, 0)>(vb); Hb[3] = tr_read<v_rd_off(D0, 3, 1)>(vb);
; #define MM(D0, Lb, Hb) o[D0] = __builtin_amdgcn_mfma_f32_32x32x16_bf16(pa0, PK(Lb[0], Hb[0]), o[D0], 0, 0, 0); o[D0] = __builtin_amdgcn_mfma_f32_32x32x16_bf16(pa1, PK(Lb[1], Hb[1]), o[D0], 0, 0, 0); \
;     o[D0] = __builtin_amdgcn_mfma_f32_32x32x16_bf16(pa2, PK(Lb[2], Hb[2]), o[D0], 0, 0, 0); o[D0] = __builtin_amdgcn_mfma_f32_32x32x16_bf16(pa3, PK(Lb[3], Hb[3]), o[D0], 0, 0, 0);
; #define KLOAD(k0) do { ks0 = *reinterpret_cast<const bf16x8*>(&Kh[(long)((k0) + sr) * LDK + sc]); ks1 = *reinterpret_cast<const bf16x8*>(&Kh[(long)((k0) + 32 + sr) * LDK + sc]); } while (0)
; #define VLOAD(k0) do { vs00 = *reinterpret_cast<const bf16x8*>(&Vh[(long)((k0) + sr) * LDK + sc]); vs01 = *reinterpret_cast<const bf16x8*>(&Vh[(long)((k0) + 32 + sr) * LDK + sc]); \
;     vs10 = *reinterpret_cast<const bf16x8*>(&Vh[(long)((k0) + sr) * LDK + 128 + sc]); vs11 = *reinterpret_cast<const bf16x8*>(&Vh[(long)((k0) + 32 + sr) * LDK + 128 + sc]); } while (0)
; __device__ __forceinline__ void pv_batched(f32x16* o, int vb, bf16x8 pa0, bf16x8 pa1, bf16x8 pa2, bf16x8 pa3) {
;   s16x4 L0[4], H0[4], L1[4], H1[4];
;     ...
;   TRD(L0, H0, 0) SBAR(); TRD(L1, H1, 1) SBAR();
;   asm volatile("s_waitcnt lgkmcnt(8)" ::: "memory"); SBAR();
;   MM(0, L0, H0) SBAR();
;   TRD(L0, H0, 2) SBAR();
;   asm volatile("s_waitcnt lgkmcnt(8)" ::: "memory"); SBAR();
;   MM(1, L1, H1) SBAR();
;   TRD(L1, H1, 3) SBAR();
;   asm volatile("s_waitcnt lgkmcnt(8)" ::: "memory"); SBAR();
;   MM(2, L0, H0) SBAR();
;   asm volatile("s_waitcnt lgkmcnt(0)" ::: "memory"); SBAR();
;   MM(3, L1, H1) SBAR();
; template <int LDQ, int LDK, int LDO>
; __device__ __forceinline__ void attn_pair_body(const bf16* __restrict__ Qb, const bf16* __restrict__ Kh, const bf16* __restrict__ Vh, float* __restrict__ Ob, int NT, char* lds, int tid_in) {
;     ...
;     KWRITE(b);
;     VWRITE(b);
;     { const int tk = j + 3 < NT ? j + 3 : NT - 1, tv = j + 1 < NT ? j + 1 : NT - 1; KLOAD(tk * KVBLK); VLOAD(tv * KVBLK); }
.Lpa_cons_pv:
	v_lshl_add_u32 v219, s21, 15, v211
	ds_read_b64_tr_b16 v[220:221], v219 offset:0
	ds_read_b64_tr_b16 v[222:223], v219 offset:0x800
	ds_read_b64_tr_b16 v[224:225], v219 offset:0x1000
	ds_read_b64_tr_b16 v[226:227], v219 offset:0x1800
	ds_read_b64_tr_b16 v[234:235], v219 offset:0x2000
	ds_read_b64_tr_b16 v[236:237], v219 offset:0x2800
	ds_read_b64_tr_b16 v[238:239], v219 offset:0x3000
	ds_read_b64_tr_b16 v[240:241], v219 offset:0x3800
	ds_read_b64_tr_b16 v[242:243], v219 offset:0x200
	ds_read_b64_tr_b16 v[244:245], v219 offset:0xa00
	ds_read_b64_tr_b16 v[246:247], v219 offset:0x1200
	ds_read_b64_tr_b16 v[248:249], v219 offset:0x1a00
	ds_read_b64_tr_b16 v[176:177], v219 offset:0x2200
	ds_read_b64_tr_b16 v[178:179], v219 offset:0x2a00
	ds_read_b64_tr_b16 v[228:229], v219 offset:0x3200
	ds_read_b64_tr_b16 v[230:231], v219 offset:0x3a00
	s_xor_b32 s28, s21, 1
	s_lshl_b32 s29, s28, 14
	s_lshl_b32 s28, s28, 15
	s_add_i32 s29, s29, s32
	s_add_i32 s28, s28, s58
	s_add_u32 s74, s74, 0x90000
	s_addc_u32 s75, s75, 0
	s_mov_b32 m0, s29
	s_add_u32 s92, s92, 0x90000
	s_addc_u32 s93, s93, 0
	global_load_lds_dwordx4 v172, s[74:75]
	s_add_i32 m0, s29, 0x400
	s_add_u32 s96, s96, 0x90000
	s_addc_u32 s97, s97, 0
	global_load_lds_dwordx4 v173, s[74:75]
	s_mov_b32 m0, s28
	s_nop 0
	global_load_lds_dwordx4 v174, s[92:93]
	s_add_i32 m0, s28, 0x380
	s_nop 0
	global_load_lds_dwordx4 v174, s[92:93] offset:128
	s_add_i32 m0, s28, 0x800
	s_nop 0
	global_load_lds_dwordx4 v174, s[96:97]
	s_add_i32 m0, s28, 0xb80
	s_nop 0
	global_load_lds_dwordx4 v174, s[96:97] offset:128
	s_waitcnt lgkmcnt(8)
	s_nop 0
	v_mfma_f32_32x32x16_bf16 v[4:19], v[168:171], v[220:223], v[4:19]
	s_waitcnt lgkmcnt(8)
	v_mfma_f32_32x32x16_bf16 v[4:19], v[164:167], v[224:227], v[4:19]
	s_waitcnt lgkmcnt(7)
	v_mfma_f32_32x32x16_bf16 v[4:19], v[160:163], v[234:237], v[4:19]
	s_waitcnt lgkmcnt(6)
	v_mfma_f32_32x32x16_bf16 v[4:19], v[156:159], v[238:241], v[4:19]
	ds_read_b64_tr_b16 v[220:221], v219 offset:0x400
	ds_read_b64_tr_b16 v[222:223], v219 offset:0xc00
	ds_read_b64_tr_b16 v[224:225], v219 offset:0x1400
	ds_read_b64_tr_b16 v[226:227], v219 offset:0x1c00
	ds_read_b64_tr_b16 v[232:233], v219 offset:0x2400
	ds_read_b64_tr_b16 v[234:235], v219 offset:0x2c00
	ds_read_b64_tr_b16 v[236:237], v219 offset:0x3400
	ds_read_b64_tr_b16 v[238:239], v219 offset:0x3c00
	s_waitcnt lgkmcnt(8)
	v_mfma_f32_32x32x16_bf16 v[52:67], v[168:171], v[242:245], v[52:67]
	v_mfma_f32_32x32x16_bf16 v[52:67], v[164:167], v[246:249], v[52:67]
	v_mfma_f32_32x32x16_bf16 v[52:67], v[160:163], v[176:179], v[52:67]
	v_mfma_f32_32x32x16_bf16 v[52:67], v[156:159], v[228:231], v[52:67]
	ds_read_b64_tr_b16 v[176:177], v219 offset:0x600
	ds_read_b64_tr_b16 v[178:179], v219 offset:0xe00
	ds_read_b64_tr_b16 v[228:229], v219 offset:0x1600
	ds_read_b64_tr_b16 v[230:231], v219 offset:0x1e00
	ds_read_b64_tr_b16 v[240:241], v219 offset:0x2600
	ds_read_b64_tr_b16 v[242:243], v219 offset:0x2e00
	ds_read_b64_tr_b16 v[244:245], v219 offset:0x3600
	ds_read_b64_tr_b16 v[246:247], v219 offset:0x3e00
	s_waitcnt lgkmcnt(8)
	v_mfma_f32_32x32x16_bf16 v[36:51], v[168:171], v[220:223], v[36:51]
	v_mfma_f32_32x32x16_bf16 v[36:51], v[164:167], v[224:227], v[36:51]
	v_mfma_f32_32x32x16_bf16 v[36:51], v[160:163], v[232:235], v[36:51]
	v_mfma_f32_32x32x16_bf16 v[36:51], v[156:159], v[236:239], v[36:51]
	s_waitcnt lgkmcnt(0)
	v_mfma_f32_32x32x16_bf16 v[20:35], v[168:171], v[176:179], v[20:35]
	v_mfma_f32_32x32x16_bf16 v[20:35], v[164:167], v[228:231], v[20:35]
	v_mfma_f32_32x32x16_bf16 v[20:35], v[160:163], v[240:243], v[20:35]
	v_mfma_f32_32x32x16_bf16 v[20:35], v[156:159], v[244:247], v[20:35]
	s_branch .LBB0_1034
.Lpa_cons_j0:
	s_xor_b32 s28, s21, 1
	s_lshl_b32 s29, s28, 14
	s_lshl_b32 s28, s28, 15
	s_add_i32 s29, s29, s32
	s_add_i32 s28, s28, s58
	s_add_u32 s74, s74, 0x90000
	s_addc_u32 s75, s75, 0
	s_mov_b32 m0, s29
	s_add_u32 s92, s92, 0x90000
	s_addc_u32 s93, s93, 0
	global_load_lds_dwordx4 v172, s[74:75]
	s_add_i32 m0, s29, 0x400
	s_add_u32 s96, s96, 0x90000
	s_addc_u32 s97, s97, 0
	global_load_lds_dwordx4 v173, s[74:75]
	s_mov_b32 m0, s28
	s_nop 0
	global_load_lds_dwordx4 v174, s[92:93]
	s_add_i32 m0, s28, 0x380
	s_nop 0
	global_load_lds_dwordx4 v174, s[92:93] offset:128
	s_add_i32 m0, s28, 0x800
	s_nop 0
	global_load_lds_dwordx4 v174, s[96:97]
	s_add_i32 m0, s28, 0xb80
	s_nop 0
	global_load_lds_dwordx4 v174, s[96:97] offset:128
	s_branch .LBB0_1034
